# attention O stores widened to dwordx4 via v_permlane32_swap pairs (plain stores)
# speedup vs baseline: 1.0310x; 1.0038x over previous
.LBB0_186:
	v_and_b32_e32 v2, 64, v203
	v_xor_b32_e32 v1, 32, v203
	v_add_u32_e32 v2, 64, v2
	v_cmp_lt_i32_e32 vcc, v1, v2
	s_lshl_b32 s4, s3, 7
	s_nop 0
	v_cndmask_b32_e32 v1, v203, v1, vcc
	v_lshlrev_b32_e32 v1, 2, v1
	ds_bpermute_b32 v1, v1, v48
	s_waitcnt lgkmcnt(0)
	v_add_f32_e32 v1, v48, v1
	v_div_scale_f32 v2, s[0:1], v1, v1, 1.0
	v_rcp_f32_e32 v3, v2
	v_readlane_b32 s0, v253, 27
	v_readlane_b32 s1, v253, 28
	v_fma_f32 v4, -v2, v3, 1.0
	v_fmac_f32_e32 v3, v4, v3
	v_div_scale_f32 v4, vcc, 1.0, v1, 1.0
	v_mul_f32_e32 v5, v4, v3
	v_fma_f32 v6, -v2, v5, v4
	v_fmac_f32_e32 v5, v6, v3
	v_fma_f32 v2, -v2, v5, v4
	v_div_fmas_f32 v2, v2, v3, v5
	v_mov_b64_e32 v[4:5], s[0:1]
	v_div_fixup_f32 v2, v2, v1, 1.0
	v_mad_i64_i32 v[4:5], s[0:1], v194, s19, v[4:5]
	v_lshl_add_u64 v[4:5], v[4:5], 0, s[4:5]
	v_lshl_add_u64 v[4:5], v[178:179], 1, v[4:5]
	v_and_b32_e32 v12, 32, v203
	v_lshrrev_b32_e32 v12, 2, v12
	v_mov_b32_e32 v13, v0
	v_lshl_add_u64 v[4:5], v[12:13], 0, v[4:5]
	v_pk_mul_f32 v[12:13], v[32:33], v[2:3] op_sel_hi:[1,0]
	v_pk_mul_f32 v[14:15], v[34:35], v[2:3] op_sel_hi:[1,0]
	v_pk_mul_f32 v[50:51], v[36:37], v[2:3] op_sel_hi:[1,0]
	v_pk_mul_f32 v[52:53], v[38:39], v[2:3] op_sel_hi:[1,0]
	v_cvt_pk_bf16_f32 v8, v12, v13
	v_cvt_pk_bf16_f32 v9, v14, v15
	v_cvt_pk_bf16_f32 v10, v50, v51
	v_cvt_pk_bf16_f32 v11, v52, v53
	s_nop 1
	v_permlane32_swap_b32_e32 v8, v10
	v_permlane32_swap_b32_e32 v9, v11
	global_store_dwordx4 v[4:5], v[8:11], off
	v_pk_mul_f32 v[12:13], v[40:41], v[2:3] op_sel_hi:[1,0]
	v_pk_mul_f32 v[14:15], v[42:43], v[2:3] op_sel_hi:[1,0]
	v_pk_mul_f32 v[50:51], v[44:45], v[2:3] op_sel_hi:[1,0]
	v_pk_mul_f32 v[52:53], v[46:47], v[2:3] op_sel_hi:[1,0]
	v_cvt_pk_bf16_f32 v8, v12, v13
	v_cvt_pk_bf16_f32 v9, v14, v15
	v_cvt_pk_bf16_f32 v10, v50, v51
	v_cvt_pk_bf16_f32 v11, v52, v53
	s_nop 1
	v_permlane32_swap_b32_e32 v8, v10
	v_permlane32_swap_b32_e32 v9, v11
	global_store_dwordx4 v[4:5], v[8:11], off offset:32
	v_pk_mul_f32 v[12:13], v[16:17], v[2:3] op_sel_hi:[1,0]
	v_pk_mul_f32 v[14:15], v[18:19], v[2:3] op_sel_hi:[1,0]
	v_pk_mul_f32 v[50:51], v[20:21], v[2:3] op_sel_hi:[1,0]
	v_pk_mul_f32 v[52:53], v[22:23], v[2:3] op_sel_hi:[1,0]
	v_cvt_pk_bf16_f32 v8, v12, v13
	v_cvt_pk_bf16_f32 v9, v14, v15
	v_cvt_pk_bf16_f32 v10, v50, v51
	v_cvt_pk_bf16_f32 v11, v52, v53
	s_nop 1
	v_permlane32_swap_b32_e32 v8, v10
	v_permlane32_swap_b32_e32 v9, v11
	global_store_dwordx4 v[4:5], v[8:11], off offset:64
	v_pk_mul_f32 v[12:13], v[24:25], v[2:3] op_sel_hi:[1,0]
	v_pk_mul_f32 v[14:15], v[26:27], v[2:3] op_sel_hi:[1,0]
	v_pk_mul_f32 v[50:51], v[28:29], v[2:3] op_sel_hi:[1,0]
	v_pk_mul_f32 v[52:53], v[30:31], v[2:3] op_sel_hi:[1,0]
	v_cvt_pk_bf16_f32 v8, v12, v13
	v_cvt_pk_bf16_f32 v9, v14, v15
	v_cvt_pk_bf16_f32 v10, v50, v51
	v_cvt_pk_bf16_f32 v11, v52, v53
	s_nop 1
	v_permlane32_swap_b32_e32 v8, v10
	v_permlane32_swap_b32_e32 v9, v11
	global_store_dwordx4 v[4:5], v[8:11], off offset:96
	s_waitcnt lgkmcnt(0)
	s_branch .LBB0_145

.LBB0_242:
	v_div_scale_f32 v2, s[20:21], v1, v1, 1.0
	v_rcp_f32_e32 v3, v2
	v_div_scale_f32 v4, vcc, 1.0, v1, 1.0
	v_fma_f32 v5, -v2, v3, 1.0
	v_fmac_f32_e32 v3, v5, v3
	v_mul_f32_e32 v5, v4, v3
	v_fma_f32 v6, -v2, v5, v4
	v_fmac_f32_e32 v5, v6, v3
	v_fma_f32 v2, -v2, v5, v4
	v_div_fmas_f32 v2, v2, v3, v5
	v_div_fixup_f32 v2, v2, v1, 1.0
	v_mad_i64_i32 v[4:5], s[20:21], v196, s19, v[190:191]
	v_and_b32_e32 v12, 32, v203
	v_lshrrev_b32_e32 v12, 2, v12
	v_mov_b32_e32 v13, v0
	v_lshl_add_u64 v[4:5], v[12:13], 0, v[4:5]
	v_pk_mul_f32 v[12:13], v[32:33], v[2:3] op_sel_hi:[1,0]
	v_pk_mul_f32 v[14:15], v[34:35], v[2:3] op_sel_hi:[1,0]
	v_pk_mul_f32 v[48:49], v[36:37], v[2:3] op_sel_hi:[1,0]
	v_pk_mul_f32 v[50:51], v[38:39], v[2:3] op_sel_hi:[1,0]
	v_cvt_pk_bf16_f32 v8, v12, v13
	v_cvt_pk_bf16_f32 v9, v14, v15
	v_cvt_pk_bf16_f32 v10, v48, v49
	v_cvt_pk_bf16_f32 v11, v50, v51
	s_nop 1
	v_permlane32_swap_b32_e32 v8, v10
	v_permlane32_swap_b32_e32 v9, v11
	global_store_dwordx4 v[4:5], v[8:11], off offset:1024
	v_pk_mul_f32 v[12:13], v[40:41], v[2:3] op_sel_hi:[1,0]
	v_pk_mul_f32 v[14:15], v[42:43], v[2:3] op_sel_hi:[1,0]
	v_pk_mul_f32 v[48:49], v[44:45], v[2:3] op_sel_hi:[1,0]
	v_pk_mul_f32 v[50:51], v[46:47], v[2:3] op_sel_hi:[1,0]
	v_cvt_pk_bf16_f32 v8, v12, v13
	v_cvt_pk_bf16_f32 v9, v14, v15
	v_cvt_pk_bf16_f32 v10, v48, v49
	v_cvt_pk_bf16_f32 v11, v50, v51
	s_nop 1
	v_permlane32_swap_b32_e32 v8, v10
	v_permlane32_swap_b32_e32 v9, v11
	global_store_dwordx4 v[4:5], v[8:11], off offset:1056
	v_pk_mul_f32 v[12:13], v[16:17], v[2:3] op_sel_hi:[1,0]
	v_pk_mul_f32 v[14:15], v[18:19], v[2:3] op_sel_hi:[1,0]
	v_pk_mul_f32 v[48:49], v[20:21], v[2:3] op_sel_hi:[1,0]
	v_pk_mul_f32 v[50:51], v[22:23], v[2:3] op_sel_hi:[1,0]
	v_cvt_pk_bf16_f32 v8, v12, v13
	v_cvt_pk_bf16_f32 v9, v14, v15
	v_cvt_pk_bf16_f32 v10, v48, v49
	v_cvt_pk_bf16_f32 v11, v50, v51
	s_nop 1
	v_permlane32_swap_b32_e32 v8, v10
	v_permlane32_swap_b32_e32 v9, v11
	global_store_dwordx4 v[4:5], v[8:11], off offset:1088
	v_pk_mul_f32 v[12:13], v[24:25], v[2:3] op_sel_hi:[1,0]
	v_pk_mul_f32 v[14:15], v[26:27], v[2:3] op_sel_hi:[1,0]
	v_pk_mul_f32 v[48:49], v[28:29], v[2:3] op_sel_hi:[1,0]
	v_pk_mul_f32 v[50:51], v[30:31], v[2:3] op_sel_hi:[1,0]
	v_cvt_pk_bf16_f32 v8, v12, v13
	v_cvt_pk_bf16_f32 v9, v14, v15
	v_cvt_pk_bf16_f32 v10, v48, v49
	v_cvt_pk_bf16_f32 v11, v50, v51
	s_nop 1
	v_permlane32_swap_b32_e32 v8, v10
	v_permlane32_swap_b32_e32 v9, v11
	global_store_dwordx4 v[4:5], v[8:11], off offset:1120
	s_branch .LBB0_202
